# SwiGLU/RowScale epilogue entry waits only for the older row-stat prefetch (vmcnt(8) instead of vmcnt(0)) so the epilogue no longer stalls on the next tile's LDS-DMA prefetch; on top of peel + saddr +
# baseline (speedup 1.0000x reference)
; __device__ __forceinline__ unsigned cvt_pk_bf16(float lo, float hi) { unsigned r; asm volatile("v_cvt_pk_bf16_f32 %0, %1, %2" : "=v"(r) : "v"(lo), "v"(hi)); return r; }
;     __device__ __forceinline__ void operator()(const f32x4 (&acc)[2][2][4][2], const Unit& u, int wr, int wc, int fr, int fq, const float (&pf)[8]) const {
;         const int row0 = u.pm * BM + wr * 64 + fr, col0 = u.pn * HALF + wc * 32 + 8 * fq;
; #pragma unroll
;         for (int ai = 0; ai < 2; ++ai)
; #pragma unroll
;             for (int m = 0; m < 4; ++m) { const int row = row0 + ai * HALF + m * 16;
;                 const float c = (float)__float_as_uint(pf[ai * 4 + m]) * (INV_D / SSQ_SCALE) + RMS_EPS_C, k1 = __builtin_amdgcn_rsqf(c) * -1.4426950408889634f;
;                 float o[8];
; #pragma unroll
;                 for (int e = 0; e < 8; ++e) { const float a = acc[ai][0][m][e >> 2][e & 3], b = acc[ai][1][m][e >> 2][e & 3];
;                     o[e] = (a * b) * __builtin_amdgcn_rcpf(__builtin_fmaf(__builtin_amdgcn_exp2f(a * k1), c, c)); }
;                 u32x4 w; w.x = cvt_pk_bf16(o[0], o[1]); w.y = cvt_pk_bf16(o[2], o[3]); w.z = cvt_pk_bf16(o[4], o[5]); w.w = cvt_pk_bf16(o[6], o[7]);
;                 *(u32x4*)(H + (size_t)row * ldh + col0) = w; }
.LBB0_88:
	s_waitcnt vmcnt(8)
	v_cvt_f32_u32_e32 v164, v164
	v_mul_f32_e32 v124, v128, v124
	v_mul_f32_e32 v116, v120, v116
	v_mul_f32_e32 v125, v129, v125
	v_fmamk_f32 v164, v164, 0x34800000, v141
	v_rsq_f32_e32 v165, v164
	v_mul_f32_e32 v117, v121, v117
	v_mul_f32_e32 v126, v130, v126
	v_mul_f32_e32 v118, v122, v118
	v_mul_f32_e32 v165, 0xbfb8aa3b, v165
	v_mul_f32_e32 v128, v165, v128
	v_mul_f32_e32 v120, v165, v120
	v_exp_f32_e32 v128, v128
	v_exp_f32_e32 v120, v120
	v_lshl_or_b32 v150, s17, 7, v154
	v_mul_f32_e32 v127, v131, v127
	v_fma_f32 v128, v128, v164, v164
	v_fma_f32 v120, v120, v164, v164
	v_rcp_f32_e32 v128, v128
	v_rcp_f32_e32 v120, v120
	v_mul_f32_e32 v119, v123, v119
	v_lshl_add_u32 v161, s16, 8, v152
	v_mul_f32_e32 v124, v128, v124
	v_mul_f32_e32 v128, v165, v129
	v_mul_f32_e32 v116, v120, v116
	v_mul_f32_e32 v120, v165, v121
	v_exp_f32_e32 v128, v128
	v_exp_f32_e32 v120, v120
	v_ashrrev_i32_e32 v151, 31, v150
	v_mul_f32_e32 v108, v112, v108
	v_fma_f32 v128, v128, v164, v164
	v_fma_f32 v120, v120, v164, v164
	v_rcp_f32_e32 v128, v128
	v_rcp_f32_e32 v120, v120
	v_mul_f32_e32 v100, v104, v100
	v_mul_f32_e32 v109, v113, v109
	v_mul_f32_e32 v125, v128, v125
	v_mul_f32_e32 v128, v165, v130
	v_mul_f32_e32 v117, v120, v117
	v_mul_f32_e32 v120, v165, v122
	v_exp_f32_e32 v128, v128
	v_exp_f32_e32 v120, v120
	v_mul_f32_e32 v110, v114, v110
	v_mul_f32_e32 v111, v115, v111
	v_fma_f32 v128, v128, v164, v164
	v_fma_f32 v120, v120, v164, v164
	v_rcp_f32_e32 v128, v128
	v_rcp_f32_e32 v120, v120
	v_mul_f32_e32 v92, v96, v92
	v_mul_f32_e32 v84, v88, v84
	v_mul_f32_e32 v126, v128, v126
	v_mul_f32_e32 v128, v165, v131
	v_mul_f32_e32 v118, v120, v118
	v_mul_f32_e32 v120, v165, v123
	v_exp_f32_e32 v128, v128
	v_exp_f32_e32 v120, v120
	v_mul_f32_e32 v93, v97, v93
	v_mul_f32_e32 v94, v98, v94
	v_fma_f32 v128, v128, v164, v164
	v_fmac_f32_e32 v164, v120, v164
	v_rcp_f32_e32 v128, v128
	v_rcp_f32_e32 v120, v164
	v_mul_f32_e32 v95, v99, v95
	v_mul_f32_e32 v76, v80, v76
	v_mul_f32_e32 v127, v128, v127
	v_mul_f32_e32 v119, v120, v119
	v_cvt_pk_bf16_f32 v120, v124, v125
	v_cvt_pk_bf16_f32 v121, v126, v127
	v_cvt_pk_bf16_f32 v122, v116, v117
	v_mov_b64_e32 v[116:117], s[48:49]
	v_cvt_pk_bf16_f32 v123, v118, v119
	v_mad_i64_i32 v[124:125], s[16:17], v161, s58, v[116:117]
	v_lshlrev_b64 v[118:119], 1, v[150:151]
	v_lshl_add_u64 v[124:125], v[124:125], 0, v[118:119]
	global_store_dwordx4 v[124:125], v[120:123], off
	v_mul_f32_e32 v68, v72, v68
	v_mul_f32_e32 v77, v81, v77
	v_cvt_f32_u32_e32 v120, v163
	v_mul_f32_e32 v78, v82, v78
	v_mul_f32_e32 v79, v83, v79
	v_mul_f32_e32 v60, v64, v60
	v_fmamk_f32 v120, v120, 0x34800000, v141
	v_rsq_f32_e32 v121, v120
	v_mul_f32_e32 v52, v56, v52
	v_mul_f32_e32 v61, v65, v61
	v_mul_f32_e32 v62, v66, v62
	v_mul_f32_e32 v121, 0xbfb8aa3b, v121
	v_mul_f32_e32 v112, v121, v112
	v_mul_f32_e32 v104, v121, v104
	v_exp_f32_e32 v112, v112
	v_exp_f32_e32 v104, v104
	v_mul_f32_e32 v63, v67, v63
	v_mul_f32_e32 v44, v48, v44
	v_fma_f32 v112, v112, v120, v120
	v_fma_f32 v104, v104, v120, v120
	v_rcp_f32_e32 v112, v112
	v_rcp_f32_e32 v104, v104
	v_mul_f32_e32 v36, v40, v36
	v_mul_f32_e32 v45, v49, v45
	v_mul_f32_e32 v108, v112, v108
	v_mul_f32_e32 v112, v121, v113
	v_mul_f32_e32 v104, v104, v100
	v_mul_f32_e32 v100, v105, v101
	v_mul_f32_e32 v101, v121, v105
	v_exp_f32_e32 v112, v112
	v_exp_f32_e32 v101, v101
	v_mul_f32_e32 v46, v50, v46
	v_mul_f32_e32 v47, v51, v47
	v_fma_f32 v112, v112, v120, v120
	v_fma_f32 v101, v101, v120, v120
	v_rcp_f32_e32 v112, v112
	v_rcp_f32_e32 v101, v101
	v_mul_f32_e32 v28, v32, v28
	v_mul_f32_e32 v20, v24, v20
	v_mul_f32_e32 v109, v112, v109
	v_mul_f32_e32 v112, v121, v114
	v_mul_f32_e32 v105, v101, v100
	v_mul_f32_e32 v101, v121, v106
	v_exp_f32_e32 v112, v112
	v_exp_f32_e32 v101, v101
	v_mul_f32_e32 v100, v106, v102
	v_mul_f32_e32 v29, v33, v29
	v_fma_f32 v112, v112, v120, v120
	v_fma_f32 v101, v101, v120, v120
	v_rcp_f32_e32 v112, v112
	v_rcp_f32_e32 v101, v101
	v_mul_f32_e32 v30, v34, v30
	v_mul_f32_e32 v31, v35, v31
	v_mul_f32_e32 v110, v112, v110
	v_mul_f32_e32 v112, v121, v115
	v_mul_f32_e32 v106, v101, v100
	v_mul_f32_e32 v101, v121, v107
	v_exp_f32_e32 v112, v112
	v_exp_f32_e32 v101, v101
	v_mul_f32_e32 v100, v107, v103
	v_or_b32_e32 v107, 16, v161
	v_fma_f32 v112, v112, v120, v120
	v_fmac_f32_e32 v120, v101, v120
	v_rcp_f32_e32 v112, v112
	v_rcp_f32_e32 v101, v120
	v_mul_f32_e32 v12, v16, v12
	v_mul_f32_e32 v4, v8, v4
	v_mul_f32_e32 v111, v112, v111
	v_mul_f32_e32 v103, v101, v100
	v_cvt_pk_bf16_f32 v100, v108, v109
	v_cvt_pk_bf16_f32 v101, v110, v111
	v_cvt_pk_bf16_f32 v102, v104, v105
	v_mad_i64_i32 v[104:105], s[16:17], v107, s58, v[116:117]
	v_lshl_add_u64 v[104:105], v[104:105], 0, v[118:119]
	v_cvt_pk_bf16_f32 v103, v106, v103
	global_store_dwordx4 v[104:105], v[100:103], off
	v_mul_f32_e32 v13, v17, v13
	v_mul_f32_e32 v14, v18, v14
	v_cvt_f32_u32_e32 v100, v162
	v_mul_f32_e32 v15, v19, v15
	s_andn2_b64 vcc, exec, s[2:3]
	v_fmamk_f32 v100, v100, 0x34800000, v141
	v_rsq_f32_e32 v101, v100
	s_nop 0
	v_mul_f32_e32 v101, 0xbfb8aa3b, v101
	v_mul_f32_e32 v96, v101, v96
	v_mul_f32_e32 v88, v101, v88
	v_exp_f32_e32 v96, v96
	v_exp_f32_e32 v88, v88
	v_fma_f32 v96, v96, v100, v100
	v_fma_f32 v88, v88, v100, v100
	v_rcp_f32_e32 v96, v96
	v_rcp_f32_e32 v88, v88
	v_mul_f32_e32 v92, v96, v92
	v_mul_f32_e32 v96, v101, v97
	v_mul_f32_e32 v88, v88, v84
	v_mul_f32_e32 v84, v89, v85
	v_mul_f32_e32 v85, v101, v89
	v_exp_f32_e32 v96, v96
	v_exp_f32_e32 v85, v85
	v_fma_f32 v96, v96, v100, v100
	v_fma_f32 v85, v85, v100, v100
	v_rcp_f32_e32 v96, v96
	v_rcp_f32_e32 v85, v85
	v_mul_f32_e32 v93, v96, v93
; __device__ __forceinline__ unsigned cvt_pk_bf16(float lo, float hi) { unsigned r; asm volatile("v_cvt_pk_bf16_f32 %0, %1, %2" : "=v"(r) : "v"(lo), "v"(hi)); return r; }
;     __device__ __forceinline__ void operator()(const f32x4 (&acc)[2][2][4][2], const Unit& u, int wr, int wc, int fr, int fq, const float (&pf)[8]) const {
;     ...
;             for (int m = 0; m < 4; ++m) { const int row = row0 + ai * HALF + m * 16;
;                 const float c = (float)__float_as_uint(pf[ai * 4 + m]) * (INV_D / SSQ_SCALE) + RMS_EPS_C, k1 = __builtin_amdgcn_rsqf(c) * -1.4426950408889634f;
;                 float o[8];
; #pragma unroll
;                 for (int e = 0; e < 8; ++e) { const float a = acc[ai][0][m][e >> 2][e & 3], b = acc[ai][1][m][e >> 2][e & 3];
;                     o[e] = (a * b) * __builtin_amdgcn_rcpf(__builtin_fmaf(__builtin_amdgcn_exp2f(a * k1), c, c)); }
;                 u32x4 w; w.x = cvt_pk_bf16(o[0], o[1]); w.y = cvt_pk_bf16(o[2], o[3]); w.z = cvt_pk_bf16(o[4], o[5]); w.w = cvt_pk_bf16(o[6], o[7]);
;                 *(u32x4*)(H + (size_t)row * ldh + col0) = w; }
	v_mul_f32_e32 v96, v101, v98
	v_mul_f32_e32 v89, v85, v84
	v_mul_f32_e32 v85, v101, v90
	v_exp_f32_e32 v96, v96
	v_exp_f32_e32 v85, v85
	v_mul_f32_e32 v84, v90, v86
	v_fma_f32 v96, v96, v100, v100
	v_fma_f32 v85, v85, v100, v100
	v_rcp_f32_e32 v96, v96
	v_rcp_f32_e32 v85, v85
	v_mul_f32_e32 v94, v96, v94
	v_mul_f32_e32 v96, v101, v99
	v_mul_f32_e32 v90, v85, v84
	v_mul_f32_e32 v85, v101, v91
	v_exp_f32_e32 v96, v96
	v_exp_f32_e32 v85, v85
	v_mul_f32_e32 v84, v91, v87
	v_or_b32_e32 v91, 32, v161
	v_fma_f32 v96, v96, v100, v100
	v_fmac_f32_e32 v100, v85, v100
	v_rcp_f32_e32 v96, v96
	v_rcp_f32_e32 v85, v100
	v_mul_f32_e32 v95, v96, v95
	v_mul_f32_e32 v87, v85, v84
	v_cvt_pk_bf16_f32 v84, v92, v93
	v_cvt_pk_bf16_f32 v85, v94, v95
	v_cvt_pk_bf16_f32 v86, v88, v89
	v_mad_i64_i32 v[88:89], s[16:17], v91, s58, v[116:117]
	v_lshl_add_u64 v[88:89], v[88:89], 0, v[118:119]
	v_cvt_pk_bf16_f32 v87, v90, v87
	global_store_dwordx4 v[88:89], v[84:87], off
	s_nop 1
	v_cvt_f32_u32_e32 v84, v160
	v_fmamk_f32 v84, v84, 0x34800000, v141
	v_rsq_f32_e32 v85, v84
	s_nop 0
	v_mul_f32_e32 v85, 0xbfb8aa3b, v85
	v_mul_f32_e32 v80, v85, v80
	v_mul_f32_e32 v72, v85, v72
	v_exp_f32_e32 v80, v80
	v_exp_f32_e32 v72, v72
	v_fma_f32 v80, v80, v84, v84
	v_fma_f32 v72, v72, v84, v84
	v_rcp_f32_e32 v80, v80
	v_rcp_f32_e32 v72, v72
	v_mul_f32_e32 v76, v80, v76
	v_mul_f32_e32 v80, v85, v81
	v_mul_f32_e32 v72, v72, v68
	v_mul_f32_e32 v68, v73, v69
	v_mul_f32_e32 v69, v85, v73
	v_exp_f32_e32 v80, v80
	v_exp_f32_e32 v69, v69
	v_fma_f32 v80, v80, v84, v84
	v_fma_f32 v69, v69, v84, v84
	v_rcp_f32_e32 v80, v80
	v_rcp_f32_e32 v69, v69
	v_mul_f32_e32 v77, v80, v77
	v_mul_f32_e32 v80, v85, v82
	v_mul_f32_e32 v73, v69, v68
	v_mul_f32_e32 v69, v85, v74
	v_exp_f32_e32 v80, v80
	v_exp_f32_e32 v69, v69
	v_mul_f32_e32 v68, v74, v70
	v_fma_f32 v80, v80, v84, v84
	v_fma_f32 v69, v69, v84, v84
	v_rcp_f32_e32 v80, v80
	v_rcp_f32_e32 v69, v69
	v_mul_f32_e32 v78, v80, v78
	v_mul_f32_e32 v80, v85, v83
	v_mul_f32_e32 v74, v69, v68
	v_mul_f32_e32 v69, v85, v75
	v_exp_f32_e32 v80, v80
	v_exp_f32_e32 v69, v69
	v_mul_f32_e32 v68, v75, v71
	v_or_b32_e32 v75, 48, v161
	v_fma_f32 v80, v80, v84, v84
	v_fmac_f32_e32 v84, v69, v84
	v_rcp_f32_e32 v80, v80
	v_rcp_f32_e32 v69, v84
	v_mul_f32_e32 v79, v80, v79
	v_mul_f32_e32 v71, v69, v68
	v_cvt_pk_bf16_f32 v68, v76, v77
	v_cvt_pk_bf16_f32 v69, v78, v79
	v_cvt_pk_bf16_f32 v70, v72, v73
	v_mad_i64_i32 v[72:73], s[16:17], v75, s58, v[116:117]
	v_lshl_add_u64 v[72:73], v[72:73], 0, v[118:119]
	v_cvt_pk_bf16_f32 v71, v74, v71
	global_store_dwordx4 v[72:73], v[68:71], off
	s_nop 1
	v_cvt_f32_u32_e32 v69, v159
	v_add_u32_e32 v68, 0x80, v161
	v_fmamk_f32 v69, v69, 0x34800000, v141
	v_rsq_f32_e32 v70, v69
	s_nop 0
	v_mul_f32_e32 v70, 0xbfb8aa3b, v70
	v_mul_f32_e32 v64, v70, v64
	v_mul_f32_e32 v56, v70, v56
	v_exp_f32_e32 v64, v64
	v_exp_f32_e32 v56, v56
	v_fma_f32 v64, v64, v69, v69
	v_fma_f32 v56, v56, v69, v69
	v_rcp_f32_e32 v64, v64
	v_rcp_f32_e32 v56, v56
	v_mul_f32_e32 v60, v64, v60
	v_mul_f32_e32 v64, v70, v65
	v_mul_f32_e32 v56, v56, v52
	v_mul_f32_e32 v52, v57, v53
	v_mul_f32_e32 v53, v70, v57
	v_exp_f32_e32 v64, v64
	v_exp_f32_e32 v53, v53
	v_fma_f32 v64, v64, v69, v69
	v_fma_f32 v53, v53, v69, v69
	v_rcp_f32_e32 v64, v64
	v_rcp_f32_e32 v53, v53
	v_mul_f32_e32 v61, v64, v61
	v_mul_f32_e32 v64, v70, v66
	v_mul_f32_e32 v57, v53, v52
	v_mul_f32_e32 v53, v70, v58
	v_exp_f32_e32 v64, v64
	v_exp_f32_e32 v53, v53
	v_mul_f32_e32 v52, v58, v54
	v_fma_f32 v64, v64, v69, v69
	v_fma_f32 v53, v53, v69, v69
	v_rcp_f32_e32 v64, v64
	v_rcp_f32_e32 v53, v53
	v_mul_f32_e32 v62, v64, v62
	v_mul_f32_e32 v64, v70, v67
	v_mul_f32_e32 v58, v53, v52
	v_mul_f32_e32 v53, v70, v59
	v_exp_f32_e32 v64, v64
	v_exp_f32_e32 v53, v53
	v_mul_f32_e32 v52, v59, v55
	v_fma_f32 v64, v64, v69, v69
	v_fmac_f32_e32 v69, v53, v69
	v_rcp_f32_e32 v64, v64
	v_rcp_f32_e32 v53, v69
	v_mul_f32_e32 v63, v64, v63
	v_mul_f32_e32 v55, v53, v52
	v_cvt_pk_bf16_f32 v52, v60, v61
	v_cvt_pk_bf16_f32 v53, v62, v63
	v_cvt_pk_bf16_f32 v54, v56, v57
	v_mad_i64_i32 v[56:57], s[16:17], v68, s58, v[116:117]
	v_lshl_add_u64 v[56:57], v[56:57], 0, v[118:119]
	v_cvt_pk_bf16_f32 v55, v58, v55
	global_store_dwordx4 v[56:57], v[52:55], off
	s_nop 1
	v_cvt_f32_u32_e32 v52, v158
	v_fmamk_f32 v52, v52, 0x34800000, v141
	v_rsq_f32_e32 v53, v52
	s_nop 0
	v_mul_f32_e32 v53, 0xbfb8aa3b, v53
	v_mul_f32_e32 v48, v53, v48
	v_mul_f32_e32 v40, v53, v40
	v_exp_f32_e32 v48, v48
	v_exp_f32_e32 v40, v40
	v_fma_f32 v48, v48, v52, v52
	v_fma_f32 v40, v40, v52, v52
	v_rcp_f32_e32 v48, v48
	v_rcp_f32_e32 v40, v40
	v_mul_f32_e32 v44, v48, v44
	v_mul_f32_e32 v48, v53, v49
	v_mul_f32_e32 v40, v40, v36
	v_mul_f32_e32 v36, v41, v37
	v_mul_f32_e32 v37, v53, v41
	v_exp_f32_e32 v48, v48
	v_exp_f32_e32 v37, v37
	v_fma_f32 v48, v48, v52, v52
	v_fma_f32 v37, v37, v52, v52
	v_rcp_f32_e32 v48, v48
	v_rcp_f32_e32 v37, v37
; __device__ __forceinline__ unsigned cvt_pk_bf16(float lo, float hi) { unsigned r; asm volatile("v_cvt_pk_bf16_f32 %0, %1, %2" : "=v"(r) : "v"(lo), "v"(hi)); return r; }
;     __device__ __forceinline__ void prefetch(const Unit& u, int wr, int fr, float (&pf)[8]) const {
; #pragma unroll
;         for (int i = 0; i < 8; ++i) pf[i] = ssq[u.pm * BM + wr * 64 + fr + (i >> 2) * HALF + (i & 3) * 16];
;     }
;     __device__ __forceinline__ void operator()(const f32x4 (&acc)[2][2][4][2], const Unit& u, int wr, int wc, int fr, int fq, const float (&pf)[8]) const {
;     ...
;             for (int m = 0; m < 4; ++m) { const int row = row0 + ai * HALF + m * 16;
;                 const float c = (float)__float_as_uint(pf[ai * 4 + m]) * (INV_D / SSQ_SCALE) + RMS_EPS_C, k1 = __builtin_amdgcn_rsqf(c) * -1.4426950408889634f;
;                 float o[8];
; #pragma unroll
;                 for (int e = 0; e < 8; ++e) { const float a = acc[ai][0][m][e >> 2][e & 3], b = acc[ai][1][m][e >> 2][e & 3];
;                     o[e] = (a * b) * __builtin_amdgcn_rcpf(__builtin_fmaf(__builtin_amdgcn_exp2f(a * k1), c, c)); }
;                 u32x4 w; w.x = cvt_pk_bf16(o[0], o[1]); w.y = cvt_pk_bf16(o[2], o[3]); w.z = cvt_pk_bf16(o[4], o[5]); w.w = cvt_pk_bf16(o[6], o[7]);
;                 *(u32x4*)(H + (size_t)row * ldh + col0) = w; }
	v_mul_f32_e32 v45, v48, v45
	v_mul_f32_e32 v48, v53, v50
	v_mul_f32_e32 v41, v37, v36
	v_mul_f32_e32 v37, v53, v42
	v_exp_f32_e32 v48, v48
	v_exp_f32_e32 v37, v37
	v_mul_f32_e32 v36, v42, v38
	v_fma_f32 v48, v48, v52, v52
	v_fma_f32 v37, v37, v52, v52
	v_rcp_f32_e32 v48, v48
	v_rcp_f32_e32 v37, v37
	v_mul_f32_e32 v46, v48, v46
	v_mul_f32_e32 v48, v53, v51
	v_mul_f32_e32 v42, v37, v36
	v_mul_f32_e32 v37, v53, v43
	v_exp_f32_e32 v48, v48
	v_exp_f32_e32 v37, v37
	v_mul_f32_e32 v36, v43, v39
	v_add_u32_e32 v43, 0x90, v161
	v_fma_f32 v48, v48, v52, v52
	v_fmac_f32_e32 v52, v37, v52
	v_rcp_f32_e32 v48, v48
	v_rcp_f32_e32 v37, v52
	v_mul_f32_e32 v47, v48, v47
	v_mul_f32_e32 v39, v37, v36
	v_cvt_pk_bf16_f32 v36, v44, v45
	v_cvt_pk_bf16_f32 v37, v46, v47
	v_cvt_pk_bf16_f32 v38, v40, v41
	v_mad_i64_i32 v[40:41], s[16:17], v43, s58, v[116:117]
	v_lshl_add_u64 v[40:41], v[40:41], 0, v[118:119]
	v_cvt_pk_bf16_f32 v39, v42, v39
	global_store_dwordx4 v[40:41], v[36:39], off
	s_nop 1
	v_cvt_f32_u32_e32 v36, v157
	v_fmamk_f32 v36, v36, 0x34800000, v141
	v_rsq_f32_e32 v37, v36
	s_nop 0
	v_mul_f32_e32 v37, 0xbfb8aa3b, v37
	v_mul_f32_e32 v32, v37, v32
	v_mul_f32_e32 v24, v37, v24
	v_exp_f32_e32 v32, v32
	v_exp_f32_e32 v24, v24
	v_fma_f32 v32, v32, v36, v36
	v_fma_f32 v24, v24, v36, v36
	v_rcp_f32_e32 v32, v32
	v_rcp_f32_e32 v24, v24
	v_mul_f32_e32 v28, v32, v28
	v_mul_f32_e32 v32, v37, v33
	v_mul_f32_e32 v24, v24, v20
	v_mul_f32_e32 v20, v25, v21
	v_mul_f32_e32 v21, v37, v25
	v_exp_f32_e32 v32, v32
	v_exp_f32_e32 v21, v21
	v_fma_f32 v32, v32, v36, v36
	v_fma_f32 v21, v21, v36, v36
	v_rcp_f32_e32 v32, v32
	v_rcp_f32_e32 v21, v21
	v_mul_f32_e32 v29, v32, v29
	v_mul_f32_e32 v32, v37, v34
	v_mul_f32_e32 v25, v21, v20
	v_mul_f32_e32 v21, v37, v26
	v_exp_f32_e32 v32, v32
	v_exp_f32_e32 v21, v21
	v_mul_f32_e32 v20, v26, v22
	v_fma_f32 v32, v32, v36, v36
	v_fma_f32 v21, v21, v36, v36
	v_rcp_f32_e32 v32, v32
	v_rcp_f32_e32 v21, v21
	v_mul_f32_e32 v30, v32, v30
	v_mul_f32_e32 v32, v37, v35
	v_mul_f32_e32 v26, v21, v20
	v_mul_f32_e32 v21, v37, v27
	v_exp_f32_e32 v32, v32
	v_exp_f32_e32 v21, v21
	v_mul_f32_e32 v20, v27, v23
	v_add_u32_e32 v27, 0xa0, v161
	v_fma_f32 v32, v32, v36, v36
	v_fmac_f32_e32 v36, v21, v36
	v_rcp_f32_e32 v32, v32
	v_rcp_f32_e32 v21, v36
	v_mul_f32_e32 v31, v32, v31
	v_mul_f32_e32 v23, v21, v20
	v_cvt_pk_bf16_f32 v20, v28, v29
	v_cvt_pk_bf16_f32 v21, v30, v31
	v_cvt_pk_bf16_f32 v22, v24, v25
	v_mad_i64_i32 v[24:25], s[16:17], v27, s58, v[116:117]
	v_lshl_add_u64 v[24:25], v[24:25], 0, v[118:119]
	v_cvt_pk_bf16_f32 v23, v26, v23
	global_store_dwordx4 v[24:25], v[20:23], off
	s_nop 1
	v_cvt_f32_u32_e32 v20, v156
	v_fmamk_f32 v20, v20, 0x34800000, v141
	v_rsq_f32_e32 v21, v20
	s_nop 0
	v_mul_f32_e32 v21, 0xbfb8aa3b, v21
	v_mul_f32_e32 v16, v21, v16
	v_mul_f32_e32 v8, v21, v8
	v_exp_f32_e32 v16, v16
	v_exp_f32_e32 v8, v8
	v_fma_f32 v16, v16, v20, v20
	v_fma_f32 v8, v8, v20, v20
	v_rcp_f32_e32 v16, v16
	v_rcp_f32_e32 v8, v8
	v_mul_f32_e32 v12, v16, v12
	v_mul_f32_e32 v16, v21, v17
	v_mul_f32_e32 v8, v8, v4
	v_mul_f32_e32 v4, v9, v5
	v_mul_f32_e32 v5, v21, v9
	v_exp_f32_e32 v16, v16
	v_exp_f32_e32 v5, v5
	v_fma_f32 v16, v16, v20, v20
	v_fma_f32 v5, v5, v20, v20
	v_rcp_f32_e32 v16, v16
	v_rcp_f32_e32 v5, v5
	v_mul_f32_e32 v13, v16, v13
	v_mul_f32_e32 v16, v21, v18
	v_mul_f32_e32 v9, v5, v4
	v_mul_f32_e32 v5, v21, v10
	v_exp_f32_e32 v16, v16
	v_exp_f32_e32 v5, v5
	v_mul_f32_e32 v4, v10, v6
	v_fma_f32 v16, v16, v20, v20
	v_fma_f32 v5, v5, v20, v20
	v_rcp_f32_e32 v16, v16
	v_rcp_f32_e32 v5, v5
	v_mul_f32_e32 v14, v16, v14
	v_mul_f32_e32 v16, v21, v19
	v_mul_f32_e32 v10, v5, v4
	v_mul_f32_e32 v5, v21, v11
	v_exp_f32_e32 v16, v16
	v_exp_f32_e32 v5, v5
	v_mul_f32_e32 v4, v11, v7
	v_add_u32_e32 v11, 0xb0, v161
	v_fma_f32 v16, v16, v20, v20
	v_fmac_f32_e32 v20, v5, v20
	v_rcp_f32_e32 v16, v16
	v_rcp_f32_e32 v5, v20
	v_mul_f32_e32 v15, v16, v15
	v_mul_f32_e32 v7, v5, v4
	v_cvt_pk_bf16_f32 v4, v12, v13
	v_cvt_pk_bf16_f32 v5, v14, v15
	v_cvt_pk_bf16_f32 v6, v8, v9
	v_mad_i64_i32 v[8:9], s[16:17], v11, s58, v[116:117]
	v_lshl_add_u64 v[8:9], v[8:9], 0, v[118:119]
	s_mov_b64 s[16:17], -1
	v_cvt_pk_bf16_f32 v7, v10, v7
	global_store_dwordx4 v[8:9], v[4:7], off
	s_cbranch_vccnz .LBB0_81
	s_nop 0
	v_lshl_add_u32 v4, s10, 8, v152
	v_readlane_b32 s2, v255, 32
	v_ashrrev_i32_e32 v5, 31, v4
	v_readlane_b32 s3, v255, 33
	s_andn2_b64 vcc, exec, s[4:5]
	s_nop 0
	v_lshl_add_u64 v[4:5], v[4:5], 2, s[2:3]
	global_load_dword v164, v[4:5], off
	global_load_dword v163, v[4:5], off offset:64
	global_load_dword v162, v[4:5], off offset:128
	global_load_dword v160, v[4:5], off offset:192
	global_load_dword v159, v[4:5], off offset:512
	global_load_dword v158, v[4:5], off offset:576
	global_load_dword v157, v[4:5], off offset:640
	global_load_dword v156, v[4:5], off offset:704
	s_cbranch_vccnz .LBB0_80
	s_barrier
	s_branch .LBB0_80

; __device__ __forceinline__ unsigned cvt_pk_bf16(float lo, float hi) { unsigned r; asm volatile("v_cvt_pk_bf16_f32 %0, %1, %2" : "=v"(r) : "v"(lo), "v"(hi)); return r; }
;     __device__ __forceinline__ void operator()(const f32x4 (&acc)[2][2][4][2], const Unit& u, int wr, int wc, int fr, int fq, const float (&pf)[8]) const {
;         const int row0 = u.pm * BM + wr * 64 + fr, col0 = u.pn * BM + wc * 32 + 8 * fq;
; #pragma unroll
;         for (int ai = 0; ai < 2; ++ai)
; #pragma unroll
;             for (int m = 0; m < 4; ++m) { const int row = row0 + ai * HALF + m * 16; const float rs = __builtin_amdgcn_rsqf((float)__float_as_uint(pf[ai * 4 + m]) * (INV_D / SSQ_SCALE) + RMS_EPS_C);
;                 bf16_t* rowp = O + (size_t)row * ldc + col0;
; #pragma unroll
;                 for (int bj = 0; bj < 2; ++bj) { const f32x4 v0 = acc[ai][bj][m][0] * rs, v1 = acc[ai][bj][m][1] * rs;
;                     u32x4 w; w.x = cvt_pk_bf16(v0[0], v0[1]); w.y = cvt_pk_bf16(v0[2], v0[3]); w.z = cvt_pk_bf16(v1[0], v1[1]); w.w = cvt_pk_bf16(v1[2], v1[3]);
;                     *(u32x4*)(rowp + bj * HALF) = w; } }
.LBB0_254:
	s_waitcnt vmcnt(8)
	v_cvt_f32_u32_e32 v150, v150
	v_lshl_or_b32 v152, s44, 8, v159
	v_lshl_add_u32 v165, s16, 8, v154
	v_ashrrev_i32_e32 v153, 31, v152
	v_fmamk_f32 v150, v150, 0x34800000, v141
	v_rsq_f32_e32 v166, v150
	v_mov_b64_e32 v[150:151], s[48:49]
	v_mad_i64_i32 v[184:185], s[18:19], v165, s33, v[150:151]
	v_lshlrev_b64 v[152:153], 1, v[152:153]
	v_lshl_add_u64 v[184:185], v[184:185], 0, v[152:153]
	v_pk_mul_f32 v[130:131], v[166:167], v[130:131] op_sel_hi:[0,1]
	v_pk_mul_f32 v[128:129], v[166:167], v[128:129] op_sel_hi:[0,1]
	v_pk_mul_f32 v[186:187], v[166:167], v[126:127] op_sel_hi:[0,1]
	v_pk_mul_f32 v[126:127], v[166:167], v[124:125] op_sel_hi:[0,1]
	v_cvt_pk_bf16_f32 v124, v128, v129
	v_cvt_pk_bf16_f32 v125, v130, v131
	v_pk_mul_f32 v[120:121], v[166:167], v[120:121] op_sel_hi:[0,1]
	v_cvt_pk_bf16_f32 v126, v126, v127
	v_cvt_pk_bf16_f32 v127, v186, v187
	global_store_dwordx4 v[184:185], v[124:127], off
	v_pk_mul_f32 v[122:123], v[166:167], v[122:123] op_sel_hi:[0,1]
	s_andn2_b64 vcc, exec, s[2:3]
	v_pk_mul_f32 v[124:125], v[166:167], v[118:119] op_sel_hi:[0,1]
	v_pk_mul_f32 v[118:119], v[166:167], v[116:117] op_sel_hi:[0,1]
	v_cvt_pk_bf16_f32 v116, v120, v121
	v_cvt_f32_u32_e32 v120, v164
	v_cvt_pk_bf16_f32 v117, v122, v123
	v_cvt_pk_bf16_f32 v118, v118, v119
	v_cvt_pk_bf16_f32 v119, v124, v125
	global_store_dwordx4 v[184:185], v[116:119], off offset:256
	s_mov_b64 s[2:3], -1
	s_nop 0
	v_fmamk_f32 v116, v120, 0x34800000, v141
	v_rsq_f32_e32 v116, v116
	v_or_b32_e32 v117, 16, v165
	v_mad_i64_i32 v[118:119], s[18:19], v117, s33, v[150:151]
	v_lshl_add_u64 v[118:119], v[118:119], 0, v[152:153]
	v_pk_mul_f32 v[114:115], v[116:117], v[114:115] op_sel_hi:[0,1]
	v_pk_mul_f32 v[112:113], v[116:117], v[112:113] op_sel_hi:[0,1]
	v_pk_mul_f32 v[120:121], v[116:117], v[110:111] op_sel_hi:[0,1]
	v_pk_mul_f32 v[110:111], v[116:117], v[108:109] op_sel_hi:[0,1]
	v_cvt_pk_bf16_f32 v108, v112, v113
	v_cvt_pk_bf16_f32 v109, v114, v115
	v_pk_mul_f32 v[104:105], v[116:117], v[104:105] op_sel_hi:[0,1]
	v_cvt_pk_bf16_f32 v110, v110, v111
	v_cvt_pk_bf16_f32 v111, v120, v121
	global_store_dwordx4 v[118:119], v[108:111], off
	v_pk_mul_f32 v[106:107], v[116:117], v[106:107] op_sel_hi:[0,1]
	s_nop 0
	v_pk_mul_f32 v[108:109], v[116:117], v[102:103] op_sel_hi:[0,1]
	v_pk_mul_f32 v[102:103], v[116:117], v[100:101] op_sel_hi:[0,1]
	v_cvt_pk_bf16_f32 v100, v104, v105
	v_cvt_f32_u32_e32 v104, v163
	v_cvt_pk_bf16_f32 v101, v106, v107
	v_cvt_pk_bf16_f32 v102, v102, v103
	v_cvt_pk_bf16_f32 v103, v108, v109
	global_store_dwordx4 v[118:119], v[100:103], off offset:256
	s_nop 1
	v_fmamk_f32 v100, v104, 0x34800000, v141
	v_rsq_f32_e32 v100, v100
	v_or_b32_e32 v101, 32, v165
	v_mad_i64_i32 v[102:103], s[18:19], v101, s33, v[150:151]
	v_lshl_add_u64 v[102:103], v[102:103], 0, v[152:153]
	v_pk_mul_f32 v[98:99], v[100:101], v[98:99] op_sel_hi:[0,1]
	v_pk_mul_f32 v[96:97], v[100:101], v[96:97] op_sel_hi:[0,1]
	v_pk_mul_f32 v[104:105], v[100:101], v[94:95] op_sel_hi:[0,1]
	v_pk_mul_f32 v[94:95], v[100:101], v[92:93] op_sel_hi:[0,1]
	v_cvt_pk_bf16_f32 v92, v96, v97
	v_cvt_pk_bf16_f32 v93, v98, v99
	v_pk_mul_f32 v[88:89], v[100:101], v[88:89] op_sel_hi:[0,1]
	v_cvt_pk_bf16_f32 v94, v94, v95
	v_cvt_pk_bf16_f32 v95, v104, v105
	global_store_dwordx4 v[102:103], v[92:95], off
	v_pk_mul_f32 v[90:91], v[100:101], v[90:91] op_sel_hi:[0,1]
	s_nop 0
	v_pk_mul_f32 v[92:93], v[100:101], v[86:87] op_sel_hi:[0,1]
	v_pk_mul_f32 v[86:87], v[100:101], v[84:85] op_sel_hi:[0,1]
	v_cvt_pk_bf16_f32 v84, v88, v89
	v_cvt_f32_u32_e32 v88, v162
	v_cvt_pk_bf16_f32 v85, v90, v91
	v_cvt_pk_bf16_f32 v86, v86, v87
	v_cvt_pk_bf16_f32 v87, v92, v93
	global_store_dwordx4 v[102:103], v[84:87], off offset:256
	s_nop 1
	v_fmamk_f32 v84, v88, 0x34800000, v141
	v_rsq_f32_e32 v84, v84
	v_or_b32_e32 v85, 48, v165
	v_mad_i64_i32 v[86:87], s[18:19], v85, s33, v[150:151]
	v_lshl_add_u64 v[86:87], v[86:87], 0, v[152:153]
	v_pk_mul_f32 v[82:83], v[84:85], v[82:83] op_sel_hi:[0,1]
	v_pk_mul_f32 v[80:81], v[84:85], v[80:81] op_sel_hi:[0,1]
	v_pk_mul_f32 v[88:89], v[84:85], v[78:79] op_sel_hi:[0,1]
	v_pk_mul_f32 v[78:79], v[84:85], v[76:77] op_sel_hi:[0,1]
	v_cvt_pk_bf16_f32 v76, v80, v81
	v_cvt_pk_bf16_f32 v77, v82, v83
	v_pk_mul_f32 v[72:73], v[84:85], v[72:73] op_sel_hi:[0,1]
	v_cvt_pk_bf16_f32 v78, v78, v79
	v_cvt_pk_bf16_f32 v79, v88, v89
	global_store_dwordx4 v[86:87], v[76:79], off
	v_pk_mul_f32 v[74:75], v[84:85], v[74:75] op_sel_hi:[0,1]
	s_nop 0
	v_pk_mul_f32 v[76:77], v[84:85], v[70:71] op_sel_hi:[0,1]
	v_pk_mul_f32 v[70:71], v[84:85], v[68:69] op_sel_hi:[0,1]
	v_cvt_pk_bf16_f32 v68, v72, v73
	v_cvt_f32_u32_e32 v72, v161
	v_cvt_pk_bf16_f32 v69, v74, v75
	v_cvt_pk_bf16_f32 v70, v70, v71
	v_cvt_pk_bf16_f32 v71, v76, v77
	global_store_dwordx4 v[86:87], v[68:71], off offset:256
	s_nop 1
	v_fmamk_f32 v68, v72, 0x34800000, v141
; __device__ __forceinline__ unsigned cvt_pk_bf16(float lo, float hi) { unsigned r; asm volatile("v_cvt_pk_bf16_f32 %0, %1, %2" : "=v"(r) : "v"(lo), "v"(hi)); return r; }
;     __device__ __forceinline__ void prefetch(const Unit& u, int wr, int fr, float (&pf)[8]) const {
; #pragma unroll
;         for (int i = 0; i < 8; ++i) pf[i] = ssq[u.pm * BM + wr * 64 + fr + (i >> 2) * HALF + (i & 3) * 16];
;     }
;     __device__ __forceinline__ void operator()(const f32x4 (&acc)[2][2][4][2], const Unit& u, int wr, int wc, int fr, int fq, const float (&pf)[8]) const {
;     ...
;             for (int m = 0; m < 4; ++m) { const int row = row0 + ai * HALF + m * 16; const float rs = __builtin_amdgcn_rsqf((float)__float_as_uint(pf[ai * 4 + m]) * (INV_D / SSQ_SCALE) + RMS_EPS_C);
;                 bf16_t* rowp = O + (size_t)row * ldc + col0;
; #pragma unroll
;                 for (int bj = 0; bj < 2; ++bj) { const f32x4 v0 = acc[ai][bj][m][0] * rs, v1 = acc[ai][bj][m][1] * rs;
;                     u32x4 w; w.x = cvt_pk_bf16(v0[0], v0[1]); w.y = cvt_pk_bf16(v0[2], v0[3]); w.z = cvt_pk_bf16(v1[0], v1[1]); w.w = cvt_pk_bf16(v1[2], v1[3]);
;                     *(u32x4*)(rowp + bj * HALF) = w; } }
	v_rsq_f32_e32 v68, v68
	v_add_u32_e32 v69, 0x80, v165
	v_mad_i64_i32 v[70:71], s[18:19], v69, s33, v[150:151]
	v_lshl_add_u64 v[70:71], v[70:71], 0, v[152:153]
	v_pk_mul_f32 v[66:67], v[68:69], v[66:67] op_sel_hi:[0,1]
	v_pk_mul_f32 v[64:65], v[68:69], v[64:65] op_sel_hi:[0,1]
	v_pk_mul_f32 v[72:73], v[68:69], v[62:63] op_sel_hi:[0,1]
	v_pk_mul_f32 v[62:63], v[68:69], v[60:61] op_sel_hi:[0,1]
	v_cvt_pk_bf16_f32 v60, v64, v65
	v_cvt_pk_bf16_f32 v61, v66, v67
	v_pk_mul_f32 v[56:57], v[68:69], v[56:57] op_sel_hi:[0,1]
	v_cvt_pk_bf16_f32 v62, v62, v63
	v_cvt_pk_bf16_f32 v63, v72, v73
	global_store_dwordx4 v[70:71], v[60:63], off
	v_pk_mul_f32 v[58:59], v[68:69], v[58:59] op_sel_hi:[0,1]
	s_nop 0
	v_pk_mul_f32 v[60:61], v[68:69], v[54:55] op_sel_hi:[0,1]
	v_pk_mul_f32 v[54:55], v[68:69], v[52:53] op_sel_hi:[0,1]
	v_cvt_pk_bf16_f32 v52, v56, v57
	v_cvt_f32_u32_e32 v56, v158
	v_cvt_pk_bf16_f32 v53, v58, v59
	v_cvt_pk_bf16_f32 v54, v54, v55
	v_cvt_pk_bf16_f32 v55, v60, v61
	global_store_dwordx4 v[70:71], v[52:55], off offset:256
	s_nop 1
	v_fmamk_f32 v52, v56, 0x34800000, v141
	v_rsq_f32_e32 v52, v52
	v_add_u32_e32 v53, 0x90, v165
	v_mad_i64_i32 v[54:55], s[18:19], v53, s33, v[150:151]
	v_lshl_add_u64 v[54:55], v[54:55], 0, v[152:153]
	v_pk_mul_f32 v[50:51], v[52:53], v[50:51] op_sel_hi:[0,1]
	v_pk_mul_f32 v[48:49], v[52:53], v[48:49] op_sel_hi:[0,1]
	v_pk_mul_f32 v[56:57], v[52:53], v[46:47] op_sel_hi:[0,1]
	v_pk_mul_f32 v[46:47], v[52:53], v[44:45] op_sel_hi:[0,1]
	v_cvt_pk_bf16_f32 v44, v48, v49
	v_cvt_pk_bf16_f32 v45, v50, v51
	v_pk_mul_f32 v[40:41], v[52:53], v[40:41] op_sel_hi:[0,1]
	v_cvt_pk_bf16_f32 v46, v46, v47
	v_cvt_pk_bf16_f32 v47, v56, v57
	global_store_dwordx4 v[54:55], v[44:47], off
	v_pk_mul_f32 v[42:43], v[52:53], v[42:43] op_sel_hi:[0,1]
	s_nop 0
	v_pk_mul_f32 v[44:45], v[52:53], v[38:39] op_sel_hi:[0,1]
	v_pk_mul_f32 v[38:39], v[52:53], v[36:37] op_sel_hi:[0,1]
	v_cvt_pk_bf16_f32 v36, v40, v41
	v_cvt_f32_u32_e32 v40, v157
	v_cvt_pk_bf16_f32 v37, v42, v43
	v_cvt_pk_bf16_f32 v38, v38, v39
	v_cvt_pk_bf16_f32 v39, v44, v45
	global_store_dwordx4 v[54:55], v[36:39], off offset:256
	s_nop 1
	v_fmamk_f32 v36, v40, 0x34800000, v141
	v_rsq_f32_e32 v36, v36
	v_add_u32_e32 v37, 0xa0, v165
	v_mad_i64_i32 v[38:39], s[18:19], v37, s33, v[150:151]
	v_lshl_add_u64 v[38:39], v[38:39], 0, v[152:153]
	v_pk_mul_f32 v[34:35], v[36:37], v[34:35] op_sel_hi:[0,1]
	v_pk_mul_f32 v[32:33], v[36:37], v[32:33] op_sel_hi:[0,1]
	v_pk_mul_f32 v[40:41], v[36:37], v[30:31] op_sel_hi:[0,1]
	v_pk_mul_f32 v[30:31], v[36:37], v[28:29] op_sel_hi:[0,1]
	v_cvt_pk_bf16_f32 v28, v32, v33
	v_cvt_pk_bf16_f32 v29, v34, v35
	v_pk_mul_f32 v[24:25], v[36:37], v[24:25] op_sel_hi:[0,1]
	v_cvt_pk_bf16_f32 v30, v30, v31
	v_cvt_pk_bf16_f32 v31, v40, v41
	global_store_dwordx4 v[38:39], v[28:31], off
	v_pk_mul_f32 v[26:27], v[36:37], v[26:27] op_sel_hi:[0,1]
	s_nop 0
	v_pk_mul_f32 v[28:29], v[36:37], v[22:23] op_sel_hi:[0,1]
	v_pk_mul_f32 v[22:23], v[36:37], v[20:21] op_sel_hi:[0,1]
	v_cvt_pk_bf16_f32 v20, v24, v25
	v_cvt_f32_u32_e32 v24, v155
	v_cvt_pk_bf16_f32 v21, v26, v27
	v_cvt_pk_bf16_f32 v22, v22, v23
	v_cvt_pk_bf16_f32 v23, v28, v29
	global_store_dwordx4 v[38:39], v[20:23], off offset:256
	s_nop 1
	v_fmamk_f32 v20, v24, 0x34800000, v141
	v_rsq_f32_e32 v20, v20
	v_add_u32_e32 v21, 0xb0, v165
	v_mad_i64_i32 v[22:23], s[18:19], v21, s33, v[150:151]
	v_lshl_add_u64 v[22:23], v[22:23], 0, v[152:153]
	v_pk_mul_f32 v[18:19], v[20:21], v[18:19] op_sel_hi:[0,1]
	v_pk_mul_f32 v[16:17], v[20:21], v[16:17] op_sel_hi:[0,1]
	v_pk_mul_f32 v[24:25], v[20:21], v[14:15] op_sel_hi:[0,1]
	v_pk_mul_f32 v[14:15], v[20:21], v[12:13] op_sel_hi:[0,1]
	v_cvt_pk_bf16_f32 v12, v16, v17
	v_cvt_pk_bf16_f32 v13, v18, v19
	v_cvt_pk_bf16_f32 v14, v14, v15
	v_cvt_pk_bf16_f32 v15, v24, v25
	global_store_dwordx4 v[22:23], v[12:15], off
	v_pk_mul_f32 v[10:11], v[20:21], v[10:11] op_sel_hi:[0,1]
	v_pk_mul_f32 v[8:9], v[20:21], v[8:9] op_sel_hi:[0,1]
	v_pk_mul_f32 v[12:13], v[20:21], v[6:7] op_sel_hi:[0,1]
	v_pk_mul_f32 v[6:7], v[20:21], v[4:5] op_sel_hi:[0,1]
	v_cvt_pk_bf16_f32 v4, v8, v9
	v_cvt_pk_bf16_f32 v5, v10, v11
	v_cvt_pk_bf16_f32 v6, v6, v7
	v_cvt_pk_bf16_f32 v7, v12, v13
	global_store_dwordx4 v[22:23], v[4:7], off offset:256
	s_cbranch_vccnz .LBB0_247
	s_nop 0
	v_lshl_add_u32 v4, s10, 8, v154
	v_ashrrev_i32_e32 v5, 31, v4
	v_lshl_add_u64 v[4:5], v[4:5], 2, s[8:9]
	global_load_dword v150, v[4:5], off
	global_load_dword v164, v[4:5], off offset:64
	global_load_dword v163, v[4:5], off offset:128
	global_load_dword v162, v[4:5], off offset:192
	global_load_dword v161, v[4:5], off offset:512
	global_load_dword v158, v[4:5], off offset:576
	global_load_dword v157, v[4:5], off offset:640
	global_load_dword v155, v[4:5], off offset:704
	s_andn2_b64 vcc, exec, s[0:1]
	s_cbranch_vccnz .LBB0_246
	s_barrier
	s_branch .LBB0_246

; __device__ __forceinline__ unsigned cvt_pk_bf16(float lo, float hi) { unsigned r; asm volatile("v_cvt_pk_bf16_f32 %0, %1, %2" : "=v"(r) : "v"(lo), "v"(hi)); return r; }
;     __device__ __forceinline__ void operator()(const f32x4 (&acc)[2][2][4][2], const Unit& u, int wr, int wc, int fr, int fq, const float (&pf)[8]) const {
;         const int row0 = u.pm * BM + wr * 64 + fr, col0 = u.pn * HALF + wc * 32 + 8 * fq;
; #pragma unroll
;         for (int ai = 0; ai < 2; ++ai)
; #pragma unroll
;             for (int m = 0; m < 4; ++m) { const int row = row0 + ai * HALF + m * 16;
;                 const float c = (float)__float_as_uint(pf[ai * 4 + m]) * (INV_D / SSQ_SCALE) + RMS_EPS_C, k1 = __builtin_amdgcn_rsqf(c) * -1.4426950408889634f;
;                 float o[8];
; #pragma unroll
;                 for (int e = 0; e < 8; ++e) { const float a = acc[ai][0][m][e >> 2][e & 3], b = acc[ai][1][m][e >> 2][e & 3];
;                     o[e] = (a * b) * __builtin_amdgcn_rcpf(__builtin_fmaf(__builtin_amdgcn_exp2f(a * k1), c, c)); }
;                 u32x4 w; w.x = cvt_pk_bf16(o[0], o[1]); w.y = cvt_pk_bf16(o[2], o[3]); w.z = cvt_pk_bf16(o[4], o[5]); w.w = cvt_pk_bf16(o[6], o[7]);
;                 *(u32x4*)(H + (size_t)row * ldh + col0) = w; }
;     }
.LBB0_570:
	s_waitcnt vmcnt(8)
	v_cvt_f32_u32_e32 v164, v164
	v_mul_f32_e32 v124, v128, v124
	v_mul_f32_e32 v116, v120, v116
	v_mul_f32_e32 v125, v129, v125
	v_fmamk_f32 v164, v164, 0x34800000, v141
	v_rsq_f32_e32 v165, v164
	v_mul_f32_e32 v117, v121, v117
	v_mul_f32_e32 v126, v130, v126
	v_mul_f32_e32 v118, v122, v118
	v_mul_f32_e32 v165, 0xbfb8aa3b, v165
	v_mul_f32_e32 v128, v165, v128
	v_mul_f32_e32 v120, v165, v120
	v_exp_f32_e32 v128, v128
	v_exp_f32_e32 v120, v120
	v_lshl_or_b32 v150, s17, 7, v154
	v_mul_f32_e32 v127, v131, v127
	v_fma_f32 v128, v128, v164, v164
	v_fma_f32 v120, v120, v164, v164
	v_rcp_f32_e32 v128, v128
	v_rcp_f32_e32 v120, v120
	v_mul_f32_e32 v119, v123, v119
	v_lshl_add_u32 v161, s16, 8, v152
	v_mul_f32_e32 v124, v128, v124
	v_mul_f32_e32 v128, v165, v129
	v_mul_f32_e32 v116, v120, v116
	v_mul_f32_e32 v120, v165, v121
	v_exp_f32_e32 v128, v128
	v_exp_f32_e32 v120, v120
	v_ashrrev_i32_e32 v151, 31, v150
	v_mul_f32_e32 v108, v112, v108
	v_fma_f32 v128, v128, v164, v164
	v_fma_f32 v120, v120, v164, v164
	v_rcp_f32_e32 v128, v128
	v_rcp_f32_e32 v120, v120
	v_mul_f32_e32 v100, v104, v100
	v_mul_f32_e32 v109, v113, v109
	v_mul_f32_e32 v125, v128, v125
	v_mul_f32_e32 v128, v165, v130
	v_mul_f32_e32 v117, v120, v117
	v_mul_f32_e32 v120, v165, v122
	v_exp_f32_e32 v128, v128
	v_exp_f32_e32 v120, v120
	v_mul_f32_e32 v110, v114, v110
	v_mul_f32_e32 v111, v115, v111
	v_fma_f32 v128, v128, v164, v164
	v_fma_f32 v120, v120, v164, v164
	v_rcp_f32_e32 v128, v128
	v_rcp_f32_e32 v120, v120
	v_mul_f32_e32 v92, v96, v92
	v_mul_f32_e32 v84, v88, v84
	v_mul_f32_e32 v126, v128, v126
	v_mul_f32_e32 v128, v165, v131
	v_mul_f32_e32 v118, v120, v118
	v_mul_f32_e32 v120, v165, v123
	v_exp_f32_e32 v128, v128
	v_exp_f32_e32 v120, v120
	v_mul_f32_e32 v93, v97, v93
	v_mul_f32_e32 v94, v98, v94
	v_fma_f32 v128, v128, v164, v164
	v_fmac_f32_e32 v164, v120, v164
	v_rcp_f32_e32 v128, v128
	v_rcp_f32_e32 v120, v164
	v_mul_f32_e32 v95, v99, v95
	v_mul_f32_e32 v76, v80, v76
	v_mul_f32_e32 v127, v128, v127
	v_mul_f32_e32 v119, v120, v119
	v_cvt_pk_bf16_f32 v120, v124, v125
	v_cvt_pk_bf16_f32 v121, v126, v127
	v_cvt_pk_bf16_f32 v122, v116, v117
	v_mov_b64_e32 v[116:117], s[48:49]
	v_cvt_pk_bf16_f32 v123, v118, v119
	v_mad_i64_i32 v[124:125], s[16:17], v161, s58, v[116:117]
	v_lshlrev_b64 v[118:119], 1, v[150:151]
	v_lshl_add_u64 v[124:125], v[124:125], 0, v[118:119]
	global_store_dwordx4 v[124:125], v[120:123], off
	v_mul_f32_e32 v68, v72, v68
	v_mul_f32_e32 v77, v81, v77
	v_cvt_f32_u32_e32 v120, v163
	v_mul_f32_e32 v78, v82, v78
	v_mul_f32_e32 v79, v83, v79
	v_mul_f32_e32 v60, v64, v60
	v_fmamk_f32 v120, v120, 0x34800000, v141
	v_rsq_f32_e32 v121, v120
	v_mul_f32_e32 v52, v56, v52
	v_mul_f32_e32 v61, v65, v61
	v_mul_f32_e32 v62, v66, v62
	v_mul_f32_e32 v121, 0xbfb8aa3b, v121
	v_mul_f32_e32 v112, v121, v112
	v_mul_f32_e32 v104, v121, v104
	v_exp_f32_e32 v112, v112
	v_exp_f32_e32 v104, v104
	v_mul_f32_e32 v63, v67, v63
	v_mul_f32_e32 v44, v48, v44
	v_fma_f32 v112, v112, v120, v120
	v_fma_f32 v104, v104, v120, v120
	v_rcp_f32_e32 v112, v112
	v_rcp_f32_e32 v104, v104
	v_mul_f32_e32 v36, v40, v36
	v_mul_f32_e32 v45, v49, v45
	v_mul_f32_e32 v108, v112, v108
	v_mul_f32_e32 v112, v121, v113
	v_mul_f32_e32 v104, v104, v100
	v_mul_f32_e32 v100, v105, v101
	v_mul_f32_e32 v101, v121, v105
	v_exp_f32_e32 v112, v112
	v_exp_f32_e32 v101, v101
	v_mul_f32_e32 v46, v50, v46
	v_mul_f32_e32 v47, v51, v47
	v_fma_f32 v112, v112, v120, v120
	v_fma_f32 v101, v101, v120, v120
	v_rcp_f32_e32 v112, v112
	v_rcp_f32_e32 v101, v101
	v_mul_f32_e32 v28, v32, v28
	v_mul_f32_e32 v20, v24, v20
	v_mul_f32_e32 v109, v112, v109
	v_mul_f32_e32 v112, v121, v114
	v_mul_f32_e32 v105, v101, v100
	v_mul_f32_e32 v101, v121, v106
	v_exp_f32_e32 v112, v112
	v_exp_f32_e32 v101, v101
	v_mul_f32_e32 v100, v106, v102
	v_mul_f32_e32 v29, v33, v29
	v_fma_f32 v112, v112, v120, v120
	v_fma_f32 v101, v101, v120, v120
	v_rcp_f32_e32 v112, v112
	v_rcp_f32_e32 v101, v101
	v_mul_f32_e32 v30, v34, v30
	v_mul_f32_e32 v31, v35, v31
	v_mul_f32_e32 v110, v112, v110
	v_mul_f32_e32 v112, v121, v115
	v_mul_f32_e32 v106, v101, v100
	v_mul_f32_e32 v101, v121, v107
	v_exp_f32_e32 v112, v112
	v_exp_f32_e32 v101, v101
	v_mul_f32_e32 v100, v107, v103
	v_or_b32_e32 v107, 16, v161
	v_fma_f32 v112, v112, v120, v120
	v_fmac_f32_e32 v120, v101, v120
	v_rcp_f32_e32 v112, v112
	v_rcp_f32_e32 v101, v120
	v_mul_f32_e32 v12, v16, v12
	v_mul_f32_e32 v4, v8, v4
	v_mul_f32_e32 v111, v112, v111
	v_mul_f32_e32 v103, v101, v100
	v_cvt_pk_bf16_f32 v100, v108, v109
	v_cvt_pk_bf16_f32 v101, v110, v111
	v_cvt_pk_bf16_f32 v102, v104, v105
	v_mad_i64_i32 v[104:105], s[16:17], v107, s58, v[116:117]
	v_lshl_add_u64 v[104:105], v[104:105], 0, v[118:119]
	v_cvt_pk_bf16_f32 v103, v106, v103
	global_store_dwordx4 v[104:105], v[100:103], off
	v_mul_f32_e32 v13, v17, v13
	v_mul_f32_e32 v14, v18, v14
	v_cvt_f32_u32_e32 v100, v162
	v_mul_f32_e32 v15, v19, v15
	s_andn2_b64 vcc, exec, s[2:3]
	v_fmamk_f32 v100, v100, 0x34800000, v141
	v_rsq_f32_e32 v101, v100
	s_nop 0
	v_mul_f32_e32 v101, 0xbfb8aa3b, v101
	v_mul_f32_e32 v96, v101, v96
	v_mul_f32_e32 v88, v101, v88
	v_exp_f32_e32 v96, v96
	v_exp_f32_e32 v88, v88
	v_fma_f32 v96, v96, v100, v100
	v_fma_f32 v88, v88, v100, v100
	v_rcp_f32_e32 v96, v96
	v_rcp_f32_e32 v88, v88
	v_mul_f32_e32 v92, v96, v92
	v_mul_f32_e32 v96, v101, v97
	v_mul_f32_e32 v88, v88, v84
	v_mul_f32_e32 v84, v89, v85
	v_mul_f32_e32 v85, v101, v89
	v_exp_f32_e32 v96, v96
	v_exp_f32_e32 v85, v85
	v_fma_f32 v96, v96, v100, v100
	v_fma_f32 v85, v85, v100, v100
	v_rcp_f32_e32 v96, v96
	v_rcp_f32_e32 v85, v85
	v_mul_f32_e32 v93, v96, v93
; __device__ __forceinline__ unsigned cvt_pk_bf16(float lo, float hi) { unsigned r; asm volatile("v_cvt_pk_bf16_f32 %0, %1, %2" : "=v"(r) : "v"(lo), "v"(hi)); return r; }
;     __device__ __forceinline__ void operator()(const f32x4 (&acc)[2][2][4][2], const Unit& u, int wr, int wc, int fr, int fq, const float (&pf)[8]) const {
;         const int row0 = u.pm * BM + wr * 64 + fr, col0 = u.pn * HALF + wc * 32 + 8 * fq;
; #pragma unroll
;         for (int ai = 0; ai < 2; ++ai)
; #pragma unroll
;             for (int m = 0; m < 4; ++m) { const int row = row0 + ai * HALF + m * 16;
;                 const float c = (float)__float_as_uint(pf[ai * 4 + m]) * (INV_D / SSQ_SCALE) + RMS_EPS_C, k1 = __builtin_amdgcn_rsqf(c) * -1.4426950408889634f;
;                 float o[8];
; #pragma unroll
;                 for (int e = 0; e < 8; ++e) { const float a = acc[ai][0][m][e >> 2][e & 3], b = acc[ai][1][m][e >> 2][e & 3];
;                     o[e] = (a * b) * __builtin_amdgcn_rcpf(__builtin_fmaf(__builtin_amdgcn_exp2f(a * k1), c, c)); }
;                 u32x4 w; w.x = cvt_pk_bf16(o[0], o[1]); w.y = cvt_pk_bf16(o[2], o[3]); w.z = cvt_pk_bf16(o[4], o[5]); w.w = cvt_pk_bf16(o[6], o[7]);
;                 *(u32x4*)(H + (size_t)row * ldh + col0) = w; }
;     }
	v_mul_f32_e32 v96, v101, v98
	v_mul_f32_e32 v89, v85, v84
	v_mul_f32_e32 v85, v101, v90
	v_exp_f32_e32 v96, v96
	v_exp_f32_e32 v85, v85
	v_mul_f32_e32 v84, v90, v86
	v_fma_f32 v96, v96, v100, v100
	v_fma_f32 v85, v85, v100, v100
	v_rcp_f32_e32 v96, v96
	v_rcp_f32_e32 v85, v85
	v_mul_f32_e32 v94, v96, v94
	v_mul_f32_e32 v96, v101, v99
	v_mul_f32_e32 v90, v85, v84
	v_mul_f32_e32 v85, v101, v91
	v_exp_f32_e32 v96, v96
	v_exp_f32_e32 v85, v85
	v_mul_f32_e32 v84, v91, v87
	v_or_b32_e32 v91, 32, v161
	v_fma_f32 v96, v96, v100, v100
	v_fmac_f32_e32 v100, v85, v100
	v_rcp_f32_e32 v96, v96
	v_rcp_f32_e32 v85, v100
	v_mul_f32_e32 v95, v96, v95
	v_mul_f32_e32 v87, v85, v84
	v_cvt_pk_bf16_f32 v84, v92, v93
	v_cvt_pk_bf16_f32 v85, v94, v95
	v_cvt_pk_bf16_f32 v86, v88, v89
	v_mad_i64_i32 v[88:89], s[16:17], v91, s58, v[116:117]
	v_lshl_add_u64 v[88:89], v[88:89], 0, v[118:119]
	v_cvt_pk_bf16_f32 v87, v90, v87
	global_store_dwordx4 v[88:89], v[84:87], off
	s_nop 1
	v_cvt_f32_u32_e32 v84, v160
	v_fmamk_f32 v84, v84, 0x34800000, v141
	v_rsq_f32_e32 v85, v84
	s_nop 0
	v_mul_f32_e32 v85, 0xbfb8aa3b, v85
	v_mul_f32_e32 v80, v85, v80
	v_mul_f32_e32 v72, v85, v72
	v_exp_f32_e32 v80, v80
	v_exp_f32_e32 v72, v72
	v_fma_f32 v80, v80, v84, v84
	v_fma_f32 v72, v72, v84, v84
	v_rcp_f32_e32 v80, v80
	v_rcp_f32_e32 v72, v72
	v_mul_f32_e32 v76, v80, v76
	v_mul_f32_e32 v80, v85, v81
	v_mul_f32_e32 v72, v72, v68
	v_mul_f32_e32 v68, v73, v69
	v_mul_f32_e32 v69, v85, v73
	v_exp_f32_e32 v80, v80
	v_exp_f32_e32 v69, v69
	v_fma_f32 v80, v80, v84, v84
	v_fma_f32 v69, v69, v84, v84
	v_rcp_f32_e32 v80, v80
	v_rcp_f32_e32 v69, v69
	v_mul_f32_e32 v77, v80, v77
	v_mul_f32_e32 v80, v85, v82
	v_mul_f32_e32 v73, v69, v68
	v_mul_f32_e32 v69, v85, v74
	v_exp_f32_e32 v80, v80
	v_exp_f32_e32 v69, v69
	v_mul_f32_e32 v68, v74, v70
	v_fma_f32 v80, v80, v84, v84
	v_fma_f32 v69, v69, v84, v84
	v_rcp_f32_e32 v80, v80
	v_rcp_f32_e32 v69, v69
	v_mul_f32_e32 v78, v80, v78
	v_mul_f32_e32 v80, v85, v83
	v_mul_f32_e32 v74, v69, v68
	v_mul_f32_e32 v69, v85, v75
	v_exp_f32_e32 v80, v80
	v_exp_f32_e32 v69, v69
	v_mul_f32_e32 v68, v75, v71
	v_or_b32_e32 v75, 48, v161
	v_fma_f32 v80, v80, v84, v84
	v_fmac_f32_e32 v84, v69, v84
	v_rcp_f32_e32 v80, v80
	v_rcp_f32_e32 v69, v84
	v_mul_f32_e32 v79, v80, v79
	v_mul_f32_e32 v71, v69, v68
	v_cvt_pk_bf16_f32 v68, v76, v77
	v_cvt_pk_bf16_f32 v69, v78, v79
	v_cvt_pk_bf16_f32 v70, v72, v73
	v_mad_i64_i32 v[72:73], s[16:17], v75, s58, v[116:117]
	v_lshl_add_u64 v[72:73], v[72:73], 0, v[118:119]
	v_cvt_pk_bf16_f32 v71, v74, v71
	global_store_dwordx4 v[72:73], v[68:71], off
	s_nop 1
	v_cvt_f32_u32_e32 v69, v159
	v_add_u32_e32 v68, 0x80, v161
	v_fmamk_f32 v69, v69, 0x34800000, v141
	v_rsq_f32_e32 v70, v69
	s_nop 0
	v_mul_f32_e32 v70, 0xbfb8aa3b, v70
	v_mul_f32_e32 v64, v70, v64
	v_mul_f32_e32 v56, v70, v56
	v_exp_f32_e32 v64, v64
	v_exp_f32_e32 v56, v56
	v_fma_f32 v64, v64, v69, v69
	v_fma_f32 v56, v56, v69, v69
	v_rcp_f32_e32 v64, v64
	v_rcp_f32_e32 v56, v56
	v_mul_f32_e32 v60, v64, v60
	v_mul_f32_e32 v64, v70, v65
	v_mul_f32_e32 v56, v56, v52
	v_mul_f32_e32 v52, v57, v53
	v_mul_f32_e32 v53, v70, v57
	v_exp_f32_e32 v64, v64
	v_exp_f32_e32 v53, v53
	v_fma_f32 v64, v64, v69, v69
	v_fma_f32 v53, v53, v69, v69
	v_rcp_f32_e32 v64, v64
	v_rcp_f32_e32 v53, v53
	v_mul_f32_e32 v61, v64, v61
	v_mul_f32_e32 v64, v70, v66
	v_mul_f32_e32 v57, v53, v52
	v_mul_f32_e32 v53, v70, v58
	v_exp_f32_e32 v64, v64
	v_exp_f32_e32 v53, v53
	v_mul_f32_e32 v52, v58, v54
	v_fma_f32 v64, v64, v69, v69
	v_fma_f32 v53, v53, v69, v69
	v_rcp_f32_e32 v64, v64
	v_rcp_f32_e32 v53, v53
	v_mul_f32_e32 v62, v64, v62
	v_mul_f32_e32 v64, v70, v67
	v_mul_f32_e32 v58, v53, v52
	v_mul_f32_e32 v53, v70, v59
	v_exp_f32_e32 v64, v64
	v_exp_f32_e32 v53, v53
	v_mul_f32_e32 v52, v59, v55
	v_fma_f32 v64, v64, v69, v69
	v_fmac_f32_e32 v69, v53, v69
	v_rcp_f32_e32 v64, v64
	v_rcp_f32_e32 v53, v69
	v_mul_f32_e32 v63, v64, v63
	v_mul_f32_e32 v55, v53, v52
	v_cvt_pk_bf16_f32 v52, v60, v61
	v_cvt_pk_bf16_f32 v53, v62, v63
	v_cvt_pk_bf16_f32 v54, v56, v57
	v_mad_i64_i32 v[56:57], s[16:17], v68, s58, v[116:117]
	v_lshl_add_u64 v[56:57], v[56:57], 0, v[118:119]
	v_cvt_pk_bf16_f32 v55, v58, v55
	global_store_dwordx4 v[56:57], v[52:55], off
	s_nop 1
	v_cvt_f32_u32_e32 v52, v158
	v_fmamk_f32 v52, v52, 0x34800000, v141
	v_rsq_f32_e32 v53, v52
	s_nop 0
	v_mul_f32_e32 v53, 0xbfb8aa3b, v53
	v_mul_f32_e32 v48, v53, v48
	v_mul_f32_e32 v40, v53, v40
	v_exp_f32_e32 v48, v48
	v_exp_f32_e32 v40, v40
	v_fma_f32 v48, v48, v52, v52
	v_fma_f32 v40, v40, v52, v52
	v_rcp_f32_e32 v48, v48
	v_rcp_f32_e32 v40, v40
	v_mul_f32_e32 v44, v48, v44
	v_mul_f32_e32 v48, v53, v49
	v_mul_f32_e32 v40, v40, v36
	v_mul_f32_e32 v36, v41, v37
	v_mul_f32_e32 v37, v53, v41
	v_exp_f32_e32 v48, v48
	v_exp_f32_e32 v37, v37
	v_fma_f32 v48, v48, v52, v52
	v_fma_f32 v37, v37, v52, v52
; __device__ __forceinline__ unsigned cvt_pk_bf16(float lo, float hi) { unsigned r; asm volatile("v_cvt_pk_bf16_f32 %0, %1, %2" : "=v"(r) : "v"(lo), "v"(hi)); return r; }
;     __device__ __forceinline__ void prefetch(const Unit& u, int wr, int fr, float (&pf)[8]) const {
; #pragma unroll
;         for (int i = 0; i < 8; ++i) pf[i] = ssq[u.pm * BM + wr * 64 + fr + (i >> 2) * HALF + (i & 3) * 16];
;     }
;     __device__ __forceinline__ void operator()(const f32x4 (&acc)[2][2][4][2], const Unit& u, int wr, int wc, int fr, int fq, const float (&pf)[8]) const {
;         const int row0 = u.pm * BM + wr * 64 + fr, col0 = u.pn * HALF + wc * 32 + 8 * fq;
; #pragma unroll
;         for (int ai = 0; ai < 2; ++ai)
; #pragma unroll
;             for (int m = 0; m < 4; ++m) { const int row = row0 + ai * HALF + m * 16;
;                 const float c = (float)__float_as_uint(pf[ai * 4 + m]) * (INV_D / SSQ_SCALE) + RMS_EPS_C, k1 = __builtin_amdgcn_rsqf(c) * -1.4426950408889634f;
;                 float o[8];
; #pragma unroll
;                 for (int e = 0; e < 8; ++e) { const float a = acc[ai][0][m][e >> 2][e & 3], b = acc[ai][1][m][e >> 2][e & 3];
;                     o[e] = (a * b) * __builtin_amdgcn_rcpf(__builtin_fmaf(__builtin_amdgcn_exp2f(a * k1), c, c)); }
;                 u32x4 w; w.x = cvt_pk_bf16(o[0], o[1]); w.y = cvt_pk_bf16(o[2], o[3]); w.z = cvt_pk_bf16(o[4], o[5]); w.w = cvt_pk_bf16(o[6], o[7]);
;                 *(u32x4*)(H + (size_t)row * ldh + col0) = w; }
;     }
	v_rcp_f32_e32 v48, v48
	v_rcp_f32_e32 v37, v37
	v_mul_f32_e32 v45, v48, v45
	v_mul_f32_e32 v48, v53, v50
	v_mul_f32_e32 v41, v37, v36
	v_mul_f32_e32 v37, v53, v42
	v_exp_f32_e32 v48, v48
	v_exp_f32_e32 v37, v37
	v_mul_f32_e32 v36, v42, v38
	v_fma_f32 v48, v48, v52, v52
	v_fma_f32 v37, v37, v52, v52
	v_rcp_f32_e32 v48, v48
	v_rcp_f32_e32 v37, v37
	v_mul_f32_e32 v46, v48, v46
	v_mul_f32_e32 v48, v53, v51
	v_mul_f32_e32 v42, v37, v36
	v_mul_f32_e32 v37, v53, v43
	v_exp_f32_e32 v48, v48
	v_exp_f32_e32 v37, v37
	v_mul_f32_e32 v36, v43, v39
	v_add_u32_e32 v43, 0x90, v161
	v_fma_f32 v48, v48, v52, v52
	v_fmac_f32_e32 v52, v37, v52
	v_rcp_f32_e32 v48, v48
	v_rcp_f32_e32 v37, v52
	v_mul_f32_e32 v47, v48, v47
	v_mul_f32_e32 v39, v37, v36
	v_cvt_pk_bf16_f32 v36, v44, v45
	v_cvt_pk_bf16_f32 v37, v46, v47
	v_cvt_pk_bf16_f32 v38, v40, v41
	v_mad_i64_i32 v[40:41], s[16:17], v43, s58, v[116:117]
	v_lshl_add_u64 v[40:41], v[40:41], 0, v[118:119]
	v_cvt_pk_bf16_f32 v39, v42, v39
	global_store_dwordx4 v[40:41], v[36:39], off
	s_nop 1
	v_cvt_f32_u32_e32 v36, v157
	v_fmamk_f32 v36, v36, 0x34800000, v141
	v_rsq_f32_e32 v37, v36
	s_nop 0
	v_mul_f32_e32 v37, 0xbfb8aa3b, v37
	v_mul_f32_e32 v32, v37, v32
	v_mul_f32_e32 v24, v37, v24
	v_exp_f32_e32 v32, v32
	v_exp_f32_e32 v24, v24
	v_fma_f32 v32, v32, v36, v36
	v_fma_f32 v24, v24, v36, v36
	v_rcp_f32_e32 v32, v32
	v_rcp_f32_e32 v24, v24
	v_mul_f32_e32 v28, v32, v28
	v_mul_f32_e32 v32, v37, v33
	v_mul_f32_e32 v24, v24, v20
	v_mul_f32_e32 v20, v25, v21
	v_mul_f32_e32 v21, v37, v25
	v_exp_f32_e32 v32, v32
	v_exp_f32_e32 v21, v21
	v_fma_f32 v32, v32, v36, v36
	v_fma_f32 v21, v21, v36, v36
	v_rcp_f32_e32 v32, v32
	v_rcp_f32_e32 v21, v21
	v_mul_f32_e32 v29, v32, v29
	v_mul_f32_e32 v32, v37, v34
	v_mul_f32_e32 v25, v21, v20
	v_mul_f32_e32 v21, v37, v26
	v_exp_f32_e32 v32, v32
	v_exp_f32_e32 v21, v21
	v_mul_f32_e32 v20, v26, v22
	v_fma_f32 v32, v32, v36, v36
	v_fma_f32 v21, v21, v36, v36
	v_rcp_f32_e32 v32, v32
	v_rcp_f32_e32 v21, v21
	v_mul_f32_e32 v30, v32, v30
	v_mul_f32_e32 v32, v37, v35
	v_mul_f32_e32 v26, v21, v20
	v_mul_f32_e32 v21, v37, v27
	v_exp_f32_e32 v32, v32
	v_exp_f32_e32 v21, v21
	v_mul_f32_e32 v20, v27, v23
	v_add_u32_e32 v27, 0xa0, v161
	v_fma_f32 v32, v32, v36, v36
	v_fmac_f32_e32 v36, v21, v36
	v_rcp_f32_e32 v32, v32
	v_rcp_f32_e32 v21, v36
	v_mul_f32_e32 v31, v32, v31
	v_mul_f32_e32 v23, v21, v20
	v_cvt_pk_bf16_f32 v20, v28, v29
	v_cvt_pk_bf16_f32 v21, v30, v31
	v_cvt_pk_bf16_f32 v22, v24, v25
	v_mad_i64_i32 v[24:25], s[16:17], v27, s58, v[116:117]
	v_lshl_add_u64 v[24:25], v[24:25], 0, v[118:119]
	v_cvt_pk_bf16_f32 v23, v26, v23
	global_store_dwordx4 v[24:25], v[20:23], off
	s_nop 1
	v_cvt_f32_u32_e32 v20, v156
	v_fmamk_f32 v20, v20, 0x34800000, v141
	v_rsq_f32_e32 v21, v20
	s_nop 0
	v_mul_f32_e32 v21, 0xbfb8aa3b, v21
	v_mul_f32_e32 v16, v21, v16
	v_mul_f32_e32 v8, v21, v8
	v_exp_f32_e32 v16, v16
	v_exp_f32_e32 v8, v8
	v_fma_f32 v16, v16, v20, v20
	v_fma_f32 v8, v8, v20, v20
	v_rcp_f32_e32 v16, v16
	v_rcp_f32_e32 v8, v8
	v_mul_f32_e32 v12, v16, v12
	v_mul_f32_e32 v16, v21, v17
	v_mul_f32_e32 v8, v8, v4
	v_mul_f32_e32 v4, v9, v5
	v_mul_f32_e32 v5, v21, v9
	v_exp_f32_e32 v16, v16
	v_exp_f32_e32 v5, v5
	v_fma_f32 v16, v16, v20, v20
	v_fma_f32 v5, v5, v20, v20
	v_rcp_f32_e32 v16, v16
	v_rcp_f32_e32 v5, v5
	v_mul_f32_e32 v13, v16, v13
	v_mul_f32_e32 v16, v21, v18
	v_mul_f32_e32 v9, v5, v4
	v_mul_f32_e32 v5, v21, v10
	v_exp_f32_e32 v16, v16
	v_exp_f32_e32 v5, v5
	v_mul_f32_e32 v4, v10, v6
	v_fma_f32 v16, v16, v20, v20
	v_fma_f32 v5, v5, v20, v20
	v_rcp_f32_e32 v16, v16
	v_rcp_f32_e32 v5, v5
	v_mul_f32_e32 v14, v16, v14
	v_mul_f32_e32 v16, v21, v19
	v_mul_f32_e32 v10, v5, v4
	v_mul_f32_e32 v5, v21, v11
	v_exp_f32_e32 v16, v16
	v_exp_f32_e32 v5, v5
	v_mul_f32_e32 v4, v11, v7
	v_add_u32_e32 v11, 0xb0, v161
	v_fma_f32 v16, v16, v20, v20
	v_fmac_f32_e32 v20, v5, v20
	v_rcp_f32_e32 v16, v16
	v_rcp_f32_e32 v5, v20
	v_mul_f32_e32 v15, v16, v15
	v_mul_f32_e32 v7, v5, v4
	v_cvt_pk_bf16_f32 v4, v12, v13
	v_cvt_pk_bf16_f32 v5, v14, v15
	v_cvt_pk_bf16_f32 v6, v8, v9
	v_mad_i64_i32 v[8:9], s[16:17], v11, s58, v[116:117]
	v_lshl_add_u64 v[8:9], v[8:9], 0, v[118:119]
	s_mov_b64 s[16:17], -1
	v_cvt_pk_bf16_f32 v7, v10, v7
	global_store_dwordx4 v[8:9], v[4:7], off
	s_cbranch_vccnz .LBB0_563
	s_nop 0
	v_lshl_add_u32 v4, s10, 8, v152
	v_ashrrev_i32_e32 v5, 31, v4
	v_lshl_add_u64 v[4:5], v[4:5], 2, s[0:1]
	global_load_dword v164, v[4:5], off
	global_load_dword v163, v[4:5], off offset:64
	global_load_dword v162, v[4:5], off offset:128
	global_load_dword v160, v[4:5], off offset:192
	global_load_dword v159, v[4:5], off offset:512
	global_load_dword v158, v[4:5], off offset:576
	global_load_dword v157, v[4:5], off offset:640
	global_load_dword v156, v[4:5], off offset:704
	s_andn2_b64 vcc, exec, s[4:5]
	s_cbranch_vccnz .LBB0_562
	s_barrier
	s_branch .LBB0_562
